# XB1: grid barrier flat release - the workgroup completing the top-level count bumps every XCD generation word itself; XCD leaders wait on their XCD word (no TOPGEN hop / re-broadcast)
# speedup vs baseline: 1.0138x; 1.0138x over previous
; __device__ __forceinline__ unsigned xb_ld(unsigned* p)              { return __hip_atomic_load(p, __ATOMIC_RELAXED, __HIP_MEMORY_SCOPE_AGENT); }
; __device__ __forceinline__ unsigned xb_add(unsigned* p, unsigned v) { return __hip_atomic_fetch_add(p, v, __ATOMIC_RELAXED, __HIP_MEMORY_SCOPE_AGENT); }
; #define XB_SPIN(cond, bar) do { unsigned _sp = 0; while (cond) { __builtin_amdgcn_s_sleep(1); \
;     if ((++_sp & 255u) == 0u) { if (xb_ld(&(bar)[XB_TMO])) break; if (_sp > XB_SPIN_CAP) { atomicAdd(&(bar)[XB_TMO], 1u); break; } } } } while (0)
; __device__ __forceinline__ void xcd_barrier(const XcdBarrier& b) {
;     ...
;         const unsigned old = xb_add(&bar[XB_XSUB(b.x)], 1u);
;         const unsigned gen = old / nloc;
;         if (old + 1u == (gen + 1u) * nloc) {
;             __builtin_amdgcn_fence(__ATOMIC_RELEASE, "agent");
;             asm volatile("s_waitcnt vmcnt(0)" ::: "memory");
;             const unsigned og = xb_add(&bar[XB_TOP], 1u);
;             const unsigned tg = og / nx;
;             if (og + 1u == (tg + 1u) * nx) xb_add(&bar[XB_TOPGEN], 1u);
;             else XB_SPIN(xb_ld(&bar[XB_TOPGEN]) == tg, bar);
;             __builtin_amdgcn_fence(__ATOMIC_ACQUIRE, "agent");
;             xb_add(&bar[XB_XGEN(b.x)], 1u);
.LBB0_426:
	s_andn2_saveexec_b64 s[6:7], s[6:7]
	s_cbranch_execz .LBB0_446
	s_mov_b64 s[6:7], exec
	buffer_wbl2 sc1
	v_mov_b32_e32 v19, v2
	s_lshl_b32 s100, s40, 2
	s_add_u32 s100, s100, 0x82400
	s_add_u32 s100, s4, s100
	s_addc_u32 s101, s5, 0
	s_waitcnt lgkmcnt(0)
	s_waitcnt vmcnt(0)
	v_mbcnt_lo_u32_b32 v2, s6, 0
	v_mbcnt_hi_u32_b32 v2, s7, v2
	v_cmp_eq_u32_e32 vcc, 0, v2
	s_and_saveexec_b64 s[8:9], vcc
	s_cbranch_execz .LBB0_429
	s_bcnt1_i32_b64 s6, s[6:7]
	v_mov_b32_e32 v5, s6
	global_atomic_add v5, v197, v5, s[4:5] offset:1024 sc0
.LBB0_429:
	s_or_b64 exec, exec, s[8:9]
	s_waitcnt vmcnt(0)
	v_readfirstlane_b32 s6, v5
	v_sub_u32_e32 v6, 0, v4
	s_mov_b64 s[14:15], -1
	v_add_u32_e32 v5, s6, v2
	v_cvt_f32_u32_e32 v2, v4
	s_add_u32 s6, s4, 0x83500
	s_addc_u32 s7, s5, 0
	v_rcp_iflag_f32_e32 v2, v2
	s_nop 0
	v_mul_f32_e32 v2, 0x4f7ffffe, v2
	v_cvt_u32_f32_e32 v2, v2
	v_mul_lo_u32 v6, v6, v2
	v_mul_hi_u32 v6, v2, v6
	v_add_u32_e32 v2, v2, v6
	v_mul_hi_u32 v2, v5, v2
	v_mul_lo_u32 v6, v2, v4
	v_sub_u32_e32 v6, v5, v6
	v_cmp_ge_u32_e32 vcc, v6, v4
	v_add_u32_e32 v7, 1, v2
	v_add_u32_e32 v5, 1, v5
	v_cndmask_b32_e32 v2, v2, v7, vcc
	v_sub_u32_e32 v7, v6, v4
	v_cndmask_b32_e32 v6, v6, v7, vcc
	v_cmp_ge_u32_e32 vcc, v6, v4
	v_add_u32_e32 v6, 1, v2
	s_nop 0
	v_cndmask_b32_e32 v2, v2, v6, vcc
	v_mul_lo_u32 v6, v4, v2
	v_add_u32_e32 v4, v6, v4
	v_cmp_ne_u32_e32 vcc, v5, v4
	v_mov_b64_e32 v[4:5], s[6:7]
	s_cbranch_vccnz .Lxb_ng_1
	s_add_u32 s98, s4, 0x82400
	s_addc_u32 s99, s5, 0
	v_mov_b32_e32 v19, 1
	global_atomic_add v3, v19, s[98:99]
	global_atomic_add v3, v19, s[98:99] offset:256
	global_atomic_add v3, v19, s[98:99] offset:512
	global_atomic_add v3, v19, s[98:99] offset:768
	global_atomic_add v3, v19, s[98:99] offset:1024
	global_atomic_add v3, v19, s[98:99] offset:1280
	global_atomic_add v3, v19, s[98:99] offset:1536
	global_atomic_add v3, v19, s[98:99] offset:1792
	global_atomic_add v3, v19, s[98:99] offset:2048
	global_atomic_add v3, v19, s[98:99] offset:2304
	global_atomic_add v3, v19, s[98:99] offset:2560
	global_atomic_add v3, v19, s[98:99] offset:2816
	global_atomic_add v3, v19, s[98:99] offset:3072
	global_atomic_add v3, v19, s[98:99] offset:3328
	global_atomic_add v3, v19, s[98:99] offset:3584
	global_atomic_add v3, v19, s[98:99] offset:3840
.Lxb_ng_1:
	s_and_saveexec_b64 s[8:9], vcc
	s_cbranch_execz .LBB0_441
	global_load_dword v4, v3, s[100:101] sc1
	s_mov_b64 s[16:17], 0
	s_waitcnt vmcnt(0)
	v_cmp_eq_u32_e32 vcc, v4, v19
	s_and_saveexec_b64 s[46:47], vcc
	s_cbranch_execz .LBB0_440
	s_add_u32 s14, s4, 0x80200
	s_addc_u32 s15, s5, 0
	s_mov_b32 s30, 1
	s_mov_b64 s[4:5], 0
	s_branch .LBB0_433

; __device__ __forceinline__ unsigned xb_ld(unsigned* p)              { return __hip_atomic_load(p, __ATOMIC_RELAXED, __HIP_MEMORY_SCOPE_AGENT); }
; #define XB_SPIN(cond, bar) do { unsigned _sp = 0; while (cond) { __builtin_amdgcn_s_sleep(1); \
;     if ((++_sp & 255u) == 0u) { if (xb_ld(&(bar)[XB_TMO])) break; if (_sp > XB_SPIN_CAP) { atomicAdd(&(bar)[XB_TMO], 1u); break; } } } } while (0)
; __device__ __forceinline__ void xcd_barrier(const XcdBarrier& b) {
;     ...
;             else XB_SPIN(xb_ld(&bar[XB_TOPGEN]) == tg, bar);
.LBB0_437:
	global_load_dword v4, v3, s[100:101] sc1
	s_add_i32 s30, s30, 1
	s_mov_b64 s[22:23], -1
	s_waitcnt vmcnt(0)
	v_cmp_ne_u32_e32 vcc, v4, v19
	s_orn2_b64 s[16:17], vcc, exec
	s_branch .LBB0_432

; __device__ __forceinline__ unsigned xb_add(unsigned* p, unsigned v) { return __hip_atomic_fetch_add(p, v, __ATOMIC_RELAXED, __HIP_MEMORY_SCOPE_AGENT); }
; __device__ __forceinline__ void xcd_barrier(const XcdBarrier& b) {
;     ...
;             __builtin_amdgcn_fence(__ATOMIC_ACQUIRE, "agent");
;             xb_add(&bar[XB_XGEN(b.x)], 1u);
;             asm volatile("s_waitcnt vmcnt(0)" ::: "memory");
.LBB0_443:
	s_or_b64 exec, exec, s[4:5]
	s_mov_b64 s[4:5], exec
	v_mbcnt_lo_u32_b32 v2, s4, 0
	v_mbcnt_hi_u32_b32 v2, s5, v2
	v_cmp_eq_u32_e32 vcc, 0, v2
	s_waitcnt vmcnt(0)
	buffer_inv sc1
	s_and_saveexec_b64 s[6:7], vcc
	s_cbranch_execz .LBB0_445
	s_add_i32 s30, s40, 0x900
	s_lshl_b64 s[8:9], s[30:31], 2
	s_add_u32 s8, s34, s8
	s_addc_u32 s9, s35, s9
	s_bcnt1_i32_b64 s4, s[4:5]
	v_mov_b32_e32 v2, s4
.LBB0_445:
	s_or_b64 exec, exec, s[6:7]
	s_waitcnt vmcnt(0)

; __device__ __forceinline__ unsigned xb_ld(unsigned* p)              { return __hip_atomic_load(p, __ATOMIC_RELAXED, __HIP_MEMORY_SCOPE_AGENT); }
; __device__ __forceinline__ unsigned xb_add(unsigned* p, unsigned v) { return __hip_atomic_fetch_add(p, v, __ATOMIC_RELAXED, __HIP_MEMORY_SCOPE_AGENT); }
; #define XB_SPIN(cond, bar) do { unsigned _sp = 0; while (cond) { __builtin_amdgcn_s_sleep(1); \
;     if ((++_sp & 255u) == 0u) { if (xb_ld(&(bar)[XB_TMO])) break; if (_sp > XB_SPIN_CAP) { atomicAdd(&(bar)[XB_TMO], 1u); break; } } } } while (0)
; __device__ __forceinline__ void xcd_barrier(const XcdBarrier& b) {
;     ...
;         const unsigned old = xb_add(&bar[XB_XSUB(b.x)], 1u);
;         const unsigned gen = old / nloc;
;         if (old + 1u == (gen + 1u) * nloc) {
;             __builtin_amdgcn_fence(__ATOMIC_RELEASE, "agent");
;             asm volatile("s_waitcnt vmcnt(0)" ::: "memory");
;             const unsigned og = xb_add(&bar[XB_TOP], 1u);
;             const unsigned tg = og / nx;
;             if (og + 1u == (tg + 1u) * nx) xb_add(&bar[XB_TOPGEN], 1u);
;             else XB_SPIN(xb_ld(&bar[XB_TOPGEN]) == tg, bar);
;             __builtin_amdgcn_fence(__ATOMIC_ACQUIRE, "agent");
;             xb_add(&bar[XB_XGEN(b.x)], 1u);
.LBB0_668:
	s_andn2_saveexec_b64 s[4:5], s[4:5]
	s_cbranch_execz .LBB0_688
	s_mov_b64 s[4:5], exec
	buffer_wbl2 sc1
	v_mov_b32_e32 v19, v2
	s_lshl_b32 s100, s40, 2
	s_add_u32 s100, s100, 0x82400
	s_add_u32 s100, s2, s100
	s_addc_u32 s101, s3, 0
	s_waitcnt lgkmcnt(0)
	s_waitcnt vmcnt(0)
	v_mbcnt_lo_u32_b32 v2, s4, 0
	v_mbcnt_hi_u32_b32 v2, s5, v2
	v_cmp_eq_u32_e32 vcc, 0, v2
	s_and_saveexec_b64 s[6:7], vcc
	s_cbranch_execz .LBB0_671
	s_bcnt1_i32_b64 s4, s[4:5]
	v_mov_b32_e32 v5, s4
	global_atomic_add v5, v197, v5, s[2:3] offset:1024 sc0
.LBB0_671:
	s_or_b64 exec, exec, s[6:7]
	s_waitcnt vmcnt(0)
	v_readfirstlane_b32 s4, v5
	v_sub_u32_e32 v6, 0, v4
	s_mov_b64 s[8:9], -1
	v_add_u32_e32 v5, s4, v2
	v_cvt_f32_u32_e32 v2, v4
	s_add_u32 s4, s2, 0x83500
	s_addc_u32 s5, s3, 0
	v_rcp_iflag_f32_e32 v2, v2
	s_nop 0
	v_mul_f32_e32 v2, 0x4f7ffffe, v2
	v_cvt_u32_f32_e32 v2, v2
	v_mul_lo_u32 v6, v6, v2
	v_mul_hi_u32 v6, v2, v6
	v_add_u32_e32 v2, v2, v6
	v_mul_hi_u32 v2, v5, v2
	v_mul_lo_u32 v6, v2, v4
	v_sub_u32_e32 v6, v5, v6
	v_cmp_ge_u32_e32 vcc, v6, v4
	v_add_u32_e32 v7, 1, v2
	v_add_u32_e32 v5, 1, v5
	v_cndmask_b32_e32 v2, v2, v7, vcc
	v_sub_u32_e32 v7, v6, v4
	v_cndmask_b32_e32 v6, v6, v7, vcc
	v_cmp_ge_u32_e32 vcc, v6, v4
	v_add_u32_e32 v6, 1, v2
	s_nop 0
	v_cndmask_b32_e32 v2, v2, v6, vcc
	v_mul_lo_u32 v6, v4, v2
	v_add_u32_e32 v4, v6, v4
	v_cmp_ne_u32_e32 vcc, v5, v4
	v_mov_b64_e32 v[4:5], s[4:5]
	s_cbranch_vccnz .Lxb_ng_2
	s_add_u32 s98, s2, 0x82400
	s_addc_u32 s99, s3, 0
	v_mov_b32_e32 v19, 1
	global_atomic_add v3, v19, s[98:99]
	global_atomic_add v3, v19, s[98:99] offset:256
	global_atomic_add v3, v19, s[98:99] offset:512
	global_atomic_add v3, v19, s[98:99] offset:768
	global_atomic_add v3, v19, s[98:99] offset:1024
	global_atomic_add v3, v19, s[98:99] offset:1280
	global_atomic_add v3, v19, s[98:99] offset:1536
	global_atomic_add v3, v19, s[98:99] offset:1792
	global_atomic_add v3, v19, s[98:99] offset:2048
	global_atomic_add v3, v19, s[98:99] offset:2304
	global_atomic_add v3, v19, s[98:99] offset:2560
	global_atomic_add v3, v19, s[98:99] offset:2816
	global_atomic_add v3, v19, s[98:99] offset:3072
	global_atomic_add v3, v19, s[98:99] offset:3328
	global_atomic_add v3, v19, s[98:99] offset:3584
	global_atomic_add v3, v19, s[98:99] offset:3840
.Lxb_ng_2:
	s_and_saveexec_b64 s[6:7], vcc
	s_cbranch_execz .LBB0_683
	global_load_dword v4, v3, s[100:101] sc1
	s_mov_b64 s[16:17], 0
	s_waitcnt vmcnt(0)
	v_cmp_eq_u32_e32 vcc, v4, v19
	s_and_saveexec_b64 s[14:15], vcc
	s_cbranch_execz .LBB0_682
	s_add_u32 s8, s2, 0x80200
	s_addc_u32 s9, s3, 0
	s_mov_b32 s30, 1
	s_mov_b64 s[2:3], 0
	s_branch .LBB0_675

; __device__ __forceinline__ unsigned xb_add(unsigned* p, unsigned v) { return __hip_atomic_fetch_add(p, v, __ATOMIC_RELAXED, __HIP_MEMORY_SCOPE_AGENT); }
; __device__ __forceinline__ void xcd_barrier(const XcdBarrier& b) {
;     ...
;             __builtin_amdgcn_fence(__ATOMIC_ACQUIRE, "agent");
;             xb_add(&bar[XB_XGEN(b.x)], 1u);
;             asm volatile("s_waitcnt vmcnt(0)" ::: "memory");
.LBB0_685:
	s_or_b64 exec, exec, s[2:3]
	s_mov_b64 s[2:3], exec
	v_mbcnt_lo_u32_b32 v2, s2, 0
	v_mbcnt_hi_u32_b32 v2, s3, v2
	v_cmp_eq_u32_e32 vcc, 0, v2
	s_waitcnt vmcnt(0)
	buffer_inv sc1
	s_and_saveexec_b64 s[4:5], vcc
	s_cbranch_execz .LBB0_687
	s_add_i32 s30, s40, 0x900
	s_lshl_b64 s[6:7], s[30:31], 2
	s_add_u32 s6, s34, s6
	s_addc_u32 s7, s35, s7
	s_bcnt1_i32_b64 s2, s[2:3]
	v_mov_b32_e32 v2, s2
.LBB0_687:
	s_or_b64 exec, exec, s[4:5]
	s_waitcnt vmcnt(0)

; __device__ __forceinline__ unsigned xb_add(unsigned* p, unsigned v) { return __hip_atomic_fetch_add(p, v, __ATOMIC_RELAXED, __HIP_MEMORY_SCOPE_AGENT); }
; __device__ __forceinline__ void xcd_barrier(const XcdBarrier& b) {
;     ...
;             __builtin_amdgcn_fence(__ATOMIC_ACQUIRE, "agent");
;             xb_add(&bar[XB_XGEN(b.x)], 1u);
;             asm volatile("s_waitcnt vmcnt(0)" ::: "memory");
.LBB0_740:
	s_or_b64 exec, exec, s[2:3]
	s_mov_b64 s[2:3], exec
	v_mbcnt_lo_u32_b32 v2, s2, 0
	v_mbcnt_hi_u32_b32 v2, s3, v2
	v_cmp_eq_u32_e32 vcc, 0, v2
	s_waitcnt vmcnt(0)
	buffer_inv sc1
	s_and_saveexec_b64 s[4:5], vcc
	s_cbranch_execz .LBB0_742
	s_add_i32 s30, s40, 0x900
	s_lshl_b64 s[6:7], s[30:31], 2
	s_add_u32 s6, s34, s6
	s_addc_u32 s7, s35, s7
	s_bcnt1_i32_b64 s2, s[2:3]
	v_mov_b32_e32 v2, s2
.LBB0_742:
	s_or_b64 exec, exec, s[4:5]
	s_waitcnt vmcnt(0)

; __device__ __forceinline__ unsigned xb_ld(unsigned* p)              { return __hip_atomic_load(p, __ATOMIC_RELAXED, __HIP_MEMORY_SCOPE_AGENT); }
; #define XB_SPIN(cond, bar) do { unsigned _sp = 0; while (cond) { __builtin_amdgcn_s_sleep(1); \
;     if ((++_sp & 255u) == 0u) { if (xb_ld(&(bar)[XB_TMO])) break; if (_sp > XB_SPIN_CAP) { atomicAdd(&(bar)[XB_TMO], 1u); break; } } } } while (0)
; __device__ __forceinline__ void xcd_barrier(const XcdBarrier& b) {
;     ...
;             else XB_SPIN(xb_ld(&bar[XB_TOPGEN]) == tg, bar);
.Lxb_ng_4:
	s_and_saveexec_b64 s[6:7], vcc
	s_cbranch_execz .LBB0_935
	global_load_dword v4, v3, s[100:101] sc1
	s_mov_b64 s[16:17], 0
	s_waitcnt vmcnt(0)
	v_cmp_eq_u32_e32 vcc, v4, v19
	s_and_saveexec_b64 s[14:15], vcc
	s_cbranch_execz .LBB0_934
	s_add_u32 s8, s2, 0x80200
	s_addc_u32 s9, s3, 0
	s_mov_b32 s41, 1
	s_mov_b64 s[2:3], 0
	s_branch .LBB0_927

; __device__ __forceinline__ unsigned xb_ld(unsigned* p)              { return __hip_atomic_load(p, __ATOMIC_RELAXED, __HIP_MEMORY_SCOPE_AGENT); }
; #define XB_SPIN(cond, bar) do { unsigned _sp = 0; while (cond) { __builtin_amdgcn_s_sleep(1); \
;     if ((++_sp & 255u) == 0u) { if (xb_ld(&(bar)[XB_TMO])) break; if (_sp > XB_SPIN_CAP) { atomicAdd(&(bar)[XB_TMO], 1u); break; } } } } while (0)
; __device__ __forceinline__ void xcd_barrier(const XcdBarrier& b) {
;     ...
;             else XB_SPIN(xb_ld(&bar[XB_TOPGEN]) == tg, bar);
.LBB0_931:
	global_load_dword v4, v3, s[100:101] sc1
	s_add_i32 s41, s41, 1
	s_mov_b64 s[22:23], -1
	s_waitcnt vmcnt(0)
	v_cmp_ne_u32_e32 vcc, v4, v19
	s_orn2_b64 s[16:17], vcc, exec
	s_branch .LBB0_926

; __device__ __forceinline__ unsigned xb_add(unsigned* p, unsigned v) { return __hip_atomic_fetch_add(p, v, __ATOMIC_RELAXED, __HIP_MEMORY_SCOPE_AGENT); }
; __device__ __forceinline__ void xcd_barrier(const XcdBarrier& b) {
;     ...
;             __builtin_amdgcn_fence(__ATOMIC_ACQUIRE, "agent");
;             xb_add(&bar[XB_XGEN(b.x)], 1u);
;             asm volatile("s_waitcnt vmcnt(0)" ::: "memory");
.LBB0_937:
	s_or_b64 exec, exec, s[2:3]
	s_mov_b64 s[2:3], exec
	v_mbcnt_lo_u32_b32 v2, s2, 0
	v_mbcnt_hi_u32_b32 v2, s3, v2
	v_cmp_eq_u32_e32 vcc, 0, v2
	s_waitcnt vmcnt(0)
	buffer_inv sc1
	s_and_saveexec_b64 s[4:5], vcc
	s_cbranch_execz .LBB0_939
	s_add_i32 s6, s40, 0x900
	s_mov_b32 s7, s31
	s_lshl_b64 s[6:7], s[6:7], 2
	s_add_u32 s6, s34, s6
	s_addc_u32 s7, s35, s7
	s_bcnt1_i32_b64 s2, s[2:3]
	v_mov_b32_e32 v2, s2
.LBB0_939:
	s_or_b64 exec, exec, s[4:5]
	s_waitcnt vmcnt(0)

; __device__ __forceinline__ unsigned xb_add(unsigned* p, unsigned v) { return __hip_atomic_fetch_add(p, v, __ATOMIC_RELAXED, __HIP_MEMORY_SCOPE_AGENT); }
; __device__ __forceinline__ void xcd_barrier(const XcdBarrier& b) {
;     ...
;             __builtin_amdgcn_fence(__ATOMIC_ACQUIRE, "agent");
;             xb_add(&bar[XB_XGEN(b.x)], 1u);
;             asm volatile("s_waitcnt vmcnt(0)" ::: "memory");
.LBB0_1042:
	s_or_b64 exec, exec, s[2:3]
	s_mov_b64 s[2:3], exec
	v_mbcnt_lo_u32_b32 v2, s2, 0
	v_mbcnt_hi_u32_b32 v2, s3, v2
	v_cmp_eq_u32_e32 vcc, 0, v2
	s_waitcnt vmcnt(0)
	buffer_inv sc1
	s_and_saveexec_b64 s[4:5], vcc
	s_cbranch_execz .LBB0_1044
	s_add_i32 s6, s40, 0x900
	s_mov_b32 s7, s31
	s_lshl_b64 s[6:7], s[6:7], 2
	s_add_u32 s6, s34, s6
	s_addc_u32 s7, s35, s7
	s_bcnt1_i32_b64 s2, s[2:3]
	v_mov_b32_e32 v2, s2
.LBB0_1044:
	s_or_b64 exec, exec, s[4:5]
	s_waitcnt vmcnt(0)

; __device__ __forceinline__ unsigned xb_ld(unsigned* p)              { return __hip_atomic_load(p, __ATOMIC_RELAXED, __HIP_MEMORY_SCOPE_AGENT); }
; __device__ __forceinline__ unsigned xb_add(unsigned* p, unsigned v) { return __hip_atomic_fetch_add(p, v, __ATOMIC_RELAXED, __HIP_MEMORY_SCOPE_AGENT); }
; #define XB_SPIN(cond, bar) do { unsigned _sp = 0; while (cond) { __builtin_amdgcn_s_sleep(1); \
;     if ((++_sp & 255u) == 0u) { if (xb_ld(&(bar)[XB_TMO])) break; if (_sp > XB_SPIN_CAP) { atomicAdd(&(bar)[XB_TMO], 1u); break; } } } } while (0)
; __device__ __forceinline__ void xcd_barrier(const XcdBarrier& b) {
;     ...
;         const unsigned old = xb_add(&bar[XB_XSUB(b.x)], 1u);
;         const unsigned gen = old / nloc;
;         if (old + 1u == (gen + 1u) * nloc) {
;             __builtin_amdgcn_fence(__ATOMIC_RELEASE, "agent");
;             asm volatile("s_waitcnt vmcnt(0)" ::: "memory");
;             const unsigned og = xb_add(&bar[XB_TOP], 1u);
;             const unsigned tg = og / nx;
;             if (og + 1u == (tg + 1u) * nx) xb_add(&bar[XB_TOPGEN], 1u);
;             else XB_SPIN(xb_ld(&bar[XB_TOPGEN]) == tg, bar);
;             __builtin_amdgcn_fence(__ATOMIC_ACQUIRE, "agent");
;             xb_add(&bar[XB_XGEN(b.x)], 1u);
.LBB0_1116:
	s_or_b64 exec, exec, s[6:7]
	s_waitcnt vmcnt(0)
	v_readfirstlane_b32 s4, v5
	v_sub_u32_e32 v6, 0, v4
	s_mov_b64 s[14:15], -1
	v_add_u32_e32 v5, s4, v2
	v_cvt_f32_u32_e32 v2, v4
	s_add_u32 s4, s2, 0x83500
	s_addc_u32 s5, s3, 0
	v_rcp_iflag_f32_e32 v2, v2
	s_nop 0
	v_mul_f32_e32 v2, 0x4f7ffffe, v2
	v_cvt_u32_f32_e32 v2, v2
	v_mul_lo_u32 v6, v6, v2
	v_mul_hi_u32 v6, v2, v6
	v_add_u32_e32 v2, v2, v6
	v_mul_hi_u32 v2, v5, v2
	v_mul_lo_u32 v6, v2, v4
	v_sub_u32_e32 v6, v5, v6
	v_cmp_ge_u32_e32 vcc, v6, v4
	v_add_u32_e32 v7, 1, v2
	v_add_u32_e32 v5, 1, v5
	v_cndmask_b32_e32 v2, v2, v7, vcc
	v_sub_u32_e32 v7, v6, v4
	v_cndmask_b32_e32 v6, v6, v7, vcc
	v_cmp_ge_u32_e32 vcc, v6, v4
	v_add_u32_e32 v6, 1, v2
	s_nop 0
	v_cndmask_b32_e32 v2, v2, v6, vcc
	v_mul_lo_u32 v6, v4, v2
	v_add_u32_e32 v4, v6, v4
	v_cmp_ne_u32_e32 vcc, v5, v4
	v_mov_b64_e32 v[4:5], s[4:5]
	s_cbranch_vccnz .Lxb_ng_6
	s_add_u32 s98, s2, 0x82400
	s_addc_u32 s99, s3, 0
	v_mov_b32_e32 v19, 1
	global_atomic_add v3, v19, s[98:99]
	global_atomic_add v3, v19, s[98:99] offset:256
	global_atomic_add v3, v19, s[98:99] offset:512
	global_atomic_add v3, v19, s[98:99] offset:768
	global_atomic_add v3, v19, s[98:99] offset:1024
	global_atomic_add v3, v19, s[98:99] offset:1280
	global_atomic_add v3, v19, s[98:99] offset:1536
	global_atomic_add v3, v19, s[98:99] offset:1792
	global_atomic_add v3, v19, s[98:99] offset:2048
	global_atomic_add v3, v19, s[98:99] offset:2304
	global_atomic_add v3, v19, s[98:99] offset:2560
	global_atomic_add v3, v19, s[98:99] offset:2816
	global_atomic_add v3, v19, s[98:99] offset:3072
	global_atomic_add v3, v19, s[98:99] offset:3328
	global_atomic_add v3, v19, s[98:99] offset:3584
	global_atomic_add v3, v19, s[98:99] offset:3840
.Lxb_ng_6:
	s_and_saveexec_b64 s[6:7], vcc
	s_cbranch_execz .LBB0_1128
	global_load_dword v4, v3, s[100:101] sc1
	s_mov_b64 s[16:17], 0
	s_waitcnt vmcnt(0)
	v_cmp_eq_u32_e32 vcc, v4, v19
	s_and_saveexec_b64 s[46:47], vcc
	s_cbranch_execz .LBB0_1127
	s_add_u32 s14, s2, 0x80200
	s_addc_u32 s15, s3, 0
	s_mov_b32 s41, 1
	s_mov_b64 s[2:3], 0
	s_branch .LBB0_1120

; __device__ __forceinline__ unsigned xb_add(unsigned* p, unsigned v) { return __hip_atomic_fetch_add(p, v, __ATOMIC_RELAXED, __HIP_MEMORY_SCOPE_AGENT); }
; __device__ __forceinline__ void xcd_barrier(const XcdBarrier& b) {
;     ...
;             __builtin_amdgcn_fence(__ATOMIC_ACQUIRE, "agent");
;             xb_add(&bar[XB_XGEN(b.x)], 1u);
;             asm volatile("s_waitcnt vmcnt(0)" ::: "memory");
.LBB0_1130:
	s_or_b64 exec, exec, s[2:3]
	s_mov_b64 s[2:3], exec
	v_mbcnt_lo_u32_b32 v2, s2, 0
	v_mbcnt_hi_u32_b32 v2, s3, v2
	v_cmp_eq_u32_e32 vcc, 0, v2
	s_waitcnt vmcnt(0)
	buffer_inv sc1
	s_and_saveexec_b64 s[4:5], vcc
	s_cbranch_execz .LBB0_1132
	s_add_i32 s6, s40, 0x900
	s_mov_b32 s7, s31
	s_lshl_b64 s[6:7], s[6:7], 2
	s_add_u32 s6, s34, s6
	s_addc_u32 s7, s35, s7
	s_bcnt1_i32_b64 s2, s[2:3]
	v_mov_b32_e32 v2, s2
.LBB0_1132:
	s_or_b64 exec, exec, s[4:5]
	s_waitcnt vmcnt(0)

; __device__ __forceinline__ unsigned xb_ld(unsigned* p)              { return __hip_atomic_load(p, __ATOMIC_RELAXED, __HIP_MEMORY_SCOPE_AGENT); }
; __device__ __forceinline__ unsigned xb_add(unsigned* p, unsigned v) { return __hip_atomic_fetch_add(p, v, __ATOMIC_RELAXED, __HIP_MEMORY_SCOPE_AGENT); }
; #define XB_SPIN(cond, bar) do { unsigned _sp = 0; while (cond) { __builtin_amdgcn_s_sleep(1); \
;     if ((++_sp & 255u) == 0u) { if (xb_ld(&(bar)[XB_TMO])) break; if (_sp > XB_SPIN_CAP) { atomicAdd(&(bar)[XB_TMO], 1u); break; } } } } while (0)
; __device__ __forceinline__ void xcd_barrier(const XcdBarrier& b) {
;     ...
;         const unsigned old = xb_add(&bar[XB_XSUB(b.x)], 1u);
;         const unsigned gen = old / nloc;
;         if (old + 1u == (gen + 1u) * nloc) {
;             __builtin_amdgcn_fence(__ATOMIC_RELEASE, "agent");
;             asm volatile("s_waitcnt vmcnt(0)" ::: "memory");
;             const unsigned og = xb_add(&bar[XB_TOP], 1u);
;             const unsigned tg = og / nx;
;             if (og + 1u == (tg + 1u) * nx) xb_add(&bar[XB_TOPGEN], 1u);
;             else XB_SPIN(xb_ld(&bar[XB_TOPGEN]) == tg, bar);
;             __builtin_amdgcn_fence(__ATOMIC_ACQUIRE, "agent");
;             xb_add(&bar[XB_XGEN(b.x)], 1u);
.LBB0_1181:
	s_andn2_saveexec_b64 s[6:7], s[6:7]
	s_cbranch_execz .LBB0_1201
	s_mov_b64 s[6:7], exec
	buffer_wbl2 sc1
	v_mov_b32_e32 v19, v2
	s_lshl_b32 s100, s40, 2
	s_add_u32 s100, s100, 0x82400
	s_add_u32 s100, s4, s100
	s_addc_u32 s101, s5, 0
	s_waitcnt lgkmcnt(0)
	s_waitcnt vmcnt(0)
	v_mbcnt_lo_u32_b32 v2, s6, 0
	v_mbcnt_hi_u32_b32 v2, s7, v2
	v_cmp_eq_u32_e32 vcc, 0, v2
	s_and_saveexec_b64 s[14:15], vcc
	s_cbranch_execz .LBB0_1184
	s_bcnt1_i32_b64 s6, s[6:7]
	v_mov_b32_e32 v5, s6
	global_atomic_add v5, v197, v5, s[4:5] offset:1024 sc0
.LBB0_1184:
	s_or_b64 exec, exec, s[14:15]
	s_waitcnt vmcnt(0)
	v_readfirstlane_b32 s6, v5
	v_sub_u32_e32 v6, 0, v4
	s_mov_b64 s[16:17], -1
	v_add_u32_e32 v5, s6, v2
	v_cvt_f32_u32_e32 v2, v4
	s_add_u32 s6, s4, 0x83500
	s_addc_u32 s7, s5, 0
	v_rcp_iflag_f32_e32 v2, v2
	s_nop 0
	v_mul_f32_e32 v2, 0x4f7ffffe, v2
	v_cvt_u32_f32_e32 v2, v2
	v_mul_lo_u32 v6, v6, v2
	v_mul_hi_u32 v6, v2, v6
	v_add_u32_e32 v2, v2, v6
	v_mul_hi_u32 v2, v5, v2
	v_mul_lo_u32 v6, v2, v4
	v_sub_u32_e32 v6, v5, v6
	v_cmp_ge_u32_e32 vcc, v6, v4
	v_add_u32_e32 v7, 1, v2
	v_add_u32_e32 v5, 1, v5
	v_cndmask_b32_e32 v2, v2, v7, vcc
	v_sub_u32_e32 v7, v6, v4
	v_cndmask_b32_e32 v6, v6, v7, vcc
	v_cmp_ge_u32_e32 vcc, v6, v4
	v_add_u32_e32 v6, 1, v2
	s_nop 0
	v_cndmask_b32_e32 v2, v2, v6, vcc
	v_mul_lo_u32 v6, v4, v2
	v_add_u32_e32 v4, v6, v4
	v_cmp_ne_u32_e32 vcc, v5, v4
	v_mov_b64_e32 v[4:5], s[6:7]
	s_cbranch_vccnz .Lxb_ng_7
	s_add_u32 s98, s4, 0x82400
	s_addc_u32 s99, s5, 0
	v_mov_b32_e32 v19, 1
	global_atomic_add v3, v19, s[98:99]
	global_atomic_add v3, v19, s[98:99] offset:256
	global_atomic_add v3, v19, s[98:99] offset:512
	global_atomic_add v3, v19, s[98:99] offset:768
	global_atomic_add v3, v19, s[98:99] offset:1024
	global_atomic_add v3, v19, s[98:99] offset:1280
	global_atomic_add v3, v19, s[98:99] offset:1536
	global_atomic_add v3, v19, s[98:99] offset:1792
	global_atomic_add v3, v19, s[98:99] offset:2048
	global_atomic_add v3, v19, s[98:99] offset:2304
	global_atomic_add v3, v19, s[98:99] offset:2560
	global_atomic_add v3, v19, s[98:99] offset:2816
	global_atomic_add v3, v19, s[98:99] offset:3072
	global_atomic_add v3, v19, s[98:99] offset:3328
	global_atomic_add v3, v19, s[98:99] offset:3584
	global_atomic_add v3, v19, s[98:99] offset:3840
.Lxb_ng_7:
	s_and_saveexec_b64 s[14:15], vcc
	s_cbranch_execz .LBB0_1196
	global_load_dword v4, v3, s[100:101] sc1
	s_mov_b64 s[16:17], 0
	s_waitcnt vmcnt(0)
	v_cmp_eq_u32_e32 vcc, v4, v19
	s_and_saveexec_b64 s[52:53], vcc
	s_cbranch_execz .LBB0_1195
	s_add_u32 s46, s4, 0x80200
	s_addc_u32 s47, s5, 0
	s_mov_b32 s41, 1
	s_mov_b64 s[4:5], 0
	s_branch .LBB0_1188

; __device__ __forceinline__ unsigned xb_add(unsigned* p, unsigned v) { return __hip_atomic_fetch_add(p, v, __ATOMIC_RELAXED, __HIP_MEMORY_SCOPE_AGENT); }
; __device__ __forceinline__ void xcd_barrier(const XcdBarrier& b) {
;     ...
;             __builtin_amdgcn_fence(__ATOMIC_ACQUIRE, "agent");
;             xb_add(&bar[XB_XGEN(b.x)], 1u);
;             asm volatile("s_waitcnt vmcnt(0)" ::: "memory");
.LBB0_1198:
	s_or_b64 exec, exec, s[4:5]
	s_mov_b64 s[4:5], exec
	v_mbcnt_lo_u32_b32 v2, s4, 0
	v_mbcnt_hi_u32_b32 v2, s5, v2
	v_cmp_eq_u32_e32 vcc, 0, v2
	s_waitcnt vmcnt(0)
	buffer_inv sc1
	s_and_saveexec_b64 s[6:7], vcc
	s_cbranch_execz .LBB0_1200
	s_add_i32 s10, s40, 0x900
	s_mov_b32 s11, s31
	s_lshl_b64 s[10:11], s[10:11], 2
	s_add_u32 s10, s34, s10
	s_addc_u32 s11, s35, s11
	s_bcnt1_i32_b64 s4, s[4:5]
	v_mov_b32_e32 v2, s4
.LBB0_1200:
	s_or_b64 exec, exec, s[6:7]
	s_waitcnt vmcnt(0)

; __device__ __forceinline__ unsigned xb_ld(unsigned* p)              { return __hip_atomic_load(p, __ATOMIC_RELAXED, __HIP_MEMORY_SCOPE_AGENT); }
; #define XB_SPIN(cond, bar) do { unsigned _sp = 0; while (cond) { __builtin_amdgcn_s_sleep(1); \
;     if ((++_sp & 255u) == 0u) { if (xb_ld(&(bar)[XB_TMO])) break; if (_sp > XB_SPIN_CAP) { atomicAdd(&(bar)[XB_TMO], 1u); break; } } } } while (0)
; __device__ __forceinline__ void xcd_barrier(const XcdBarrier& b) {
;     ...
;             else XB_SPIN(xb_ld(&bar[XB_TOPGEN]) == tg, bar);
.Lxb_ng_8:
	s_and_saveexec_b64 s[6:7], vcc
	s_cbranch_execz .LBB0_1290
	global_load_dword v4, v3, s[100:101] sc1
	s_mov_b64 s[16:17], 0
	s_waitcnt vmcnt(0)
	v_cmp_eq_u32_e32 vcc, v4, v19
	s_and_saveexec_b64 s[46:47], vcc
	s_cbranch_execz .LBB0_1289
	s_add_u32 s14, s2, 0x80200
	s_addc_u32 s15, s3, 0
	s_mov_b32 s30, 1
	s_mov_b64 s[2:3], 0
	s_branch .LBB0_1282

; __device__ __forceinline__ unsigned xb_add(unsigned* p, unsigned v) { return __hip_atomic_fetch_add(p, v, __ATOMIC_RELAXED, __HIP_MEMORY_SCOPE_AGENT); }
; __device__ __forceinline__ void xcd_barrier(const XcdBarrier& b) {
;     ...
;             __builtin_amdgcn_fence(__ATOMIC_ACQUIRE, "agent");
;             xb_add(&bar[XB_XGEN(b.x)], 1u);
;             asm volatile("s_waitcnt vmcnt(0)" ::: "memory");
.LBB0_1292:
	s_or_b64 exec, exec, s[2:3]
	s_mov_b64 s[2:3], exec
	v_mbcnt_lo_u32_b32 v2, s2, 0
	v_mbcnt_hi_u32_b32 v2, s3, v2
	v_cmp_eq_u32_e32 vcc, 0, v2
	s_waitcnt vmcnt(0)
	buffer_inv sc1
	s_and_saveexec_b64 s[4:5], vcc
	s_cbranch_execz .LBB0_1294
	s_add_i32 s30, s40, 0x900
	s_lshl_b64 s[6:7], s[30:31], 2
	s_add_u32 s6, s34, s6
	s_addc_u32 s7, s35, s7
	s_bcnt1_i32_b64 s2, s[2:3]
	v_mov_b32_e32 v2, s2
.LBB0_1294:
	s_or_b64 exec, exec, s[4:5]
	s_waitcnt vmcnt(0)
